# attn unit epilogue (inst1): learned lambda computed once per workgroup instead of per unit per wave (4 loads + 12 dependent cross-lane steps removed from each unit)
# baseline (speedup 1.0000x reference)
; __device__ __forceinline__ int fresh_tid(int wave_s) { unsigned m = ~0u; asm volatile("" : "+s"(m)); int t = wave_s * 64 + (int)__builtin_amdgcn_mbcnt_hi(m, __builtin_amdgcn_mbcnt_lo(m, 0u)); asm volatile("" : "+v"(t)); return t; }
; __device__ __forceinline__ unsigned xb_xcc_id() { return (unsigned)__builtin_amdgcn_s_getreg((3 << 11) | 20) & 0xFu; }
; template <bool SAMPLE> __device__ __forceinline__ void attn_unit16(const Ctx& c, LAS unsigned char* lds, int b, int h, int qb, int wave_s) {
;     ...
;         { const float a = c.lq1[lane2] * c.lk1[lane2], bb = c.lq2[lane2] * c.lk2[lane2]; lam = __expf(wave_sum(a)) - __expf(wave_sum(bb)) + 0.2f; }
; __global__ void __launch_bounds__(512, 2) hybrid_fwd(Ctx c) {
;     ...
;         const int x0 = (int)(xb_xcc_id() & 7u);
;         for (int kx = 0; kx < 8; ++kx) {
;             const int xq = (x0 + kx) & 7;
;             for (;;) {
;                 if (fresh_tid(wave0) == 0) MISC[16] = atomicAdd(ctl + CW_XQ + 64 * xq, 1u);
.LBB0_812:
	s_add_u32 s58, s34, 0x8400
	s_addc_u32 s59, s35, 0
	s_add_u32 s4, s34, 0x13800000
	s_addc_u32 s5, s35, 0
	s_add_u32 s6, s34, 0x17900000
	s_addc_u32 s7, s35, 0
	s_add_u32 s8, s34, 0x17905080
	s_getreg_b32 s57, hwreg(HW_REG_XCC_ID, 0, 4)
	s_addc_u32 s9, s35, 0
	s_add_i32 s65, 0, 0x23040
	s_mov_b32 s64, 0
	v_mov_b32_e32 v1, 0
	v_mov_b32_e32 v204, s65
	s_movk_i32 s66, 0x100
	s_movk_i32 s67, 0x80
	s_movk_i32 s68, 0x5b
	s_movk_i32 s69, 0x1000
	s_movk_i32 s70, 0x110
	s_add_i32 s71, 0, 0x11800
	s_mov_b32 s72, 0x42200000
	s_movk_i32 s73, 0x120
	s_mov_b32 s74, 0x42700000
	s_mov_b64 s[10:11], 0x8000
	v_mov_b32_e32 v205, 0x3727c5ac
	s_mov_b32 s75, 0xf800000
	v_mov_b32_e32 v206, 0x260
	s_movk_i32 s76, 0x7fff
	v_mov_b32_e32 v207, 0x2010
	v_mov_b32_e32 v208, 0x201000
	v_mov_b32_e32 v209, 0xff
	s_mov_b32 s77, s57
	v_readlane_b32 s91, v255, 6
	v_readlane_b32 s94, v255, 5
	v_lshlrev_b32_e32 v2, 2, v212
	global_load_dword v3, v2, s[18:19]
	global_load_dword v4, v2, s[20:21]
	global_load_dword v5, v2, s[22:23]
	global_load_dword v6, v2, s[24:25]
	v_xor_b32_e32 v7, 1, v212
	v_lshlrev_b32_e32 v7, 2, v7
	v_xor_b32_e32 v8, 2, v212
	v_lshlrev_b32_e32 v8, 2, v8
	v_xor_b32_e32 v9, 4, v212
	v_lshlrev_b32_e32 v9, 2, v9
	v_xor_b32_e32 v10, 8, v212
	v_lshlrev_b32_e32 v10, 2, v10
	v_xor_b32_e32 v11, 16, v212
	v_lshlrev_b32_e32 v11, 2, v11
	v_xor_b32_e32 v12, 32, v212
	v_lshlrev_b32_e32 v12, 2, v12
	s_waitcnt vmcnt(0)
	v_mul_f32_e32 v13, v3, v4
	v_mul_f32_e32 v14, v5, v6
	ds_bpermute_b32 v13, v7, v13
	ds_bpermute_b32 v14, v7, v14
	s_waitcnt lgkmcnt(0)
	v_fmac_f32_e32 v13, v3, v4
	v_fmac_f32_e32 v14, v5, v6
	ds_bpermute_b32 v15, v8, v13
	ds_bpermute_b32 v16, v8, v14
	s_waitcnt lgkmcnt(0)
	v_add_f32_e32 v13, v13, v15
	v_add_f32_e32 v14, v14, v16
	ds_bpermute_b32 v15, v9, v13
	ds_bpermute_b32 v16, v9, v14
	s_waitcnt lgkmcnt(0)
	v_add_f32_e32 v13, v13, v15
	v_add_f32_e32 v14, v14, v16
	ds_bpermute_b32 v15, v10, v13
	ds_bpermute_b32 v16, v10, v14
	s_waitcnt lgkmcnt(0)
	v_add_f32_e32 v13, v13, v15
	v_add_f32_e32 v14, v14, v16
	ds_bpermute_b32 v15, v11, v13
	ds_bpermute_b32 v16, v11, v14
	s_waitcnt lgkmcnt(0)
	v_add_f32_e32 v13, v13, v15
	v_add_f32_e32 v14, v14, v16
	ds_bpermute_b32 v15, v12, v13
	ds_bpermute_b32 v16, v12, v14
	s_waitcnt lgkmcnt(0)
	v_add_f32_e32 v13, v13, v15
	v_add_f32_e32 v14, v14, v16
	v_mul_f32_e32 v13, 0x3fb8aa3b, v13
	v_mul_f32_e32 v14, 0x3fb8aa3b, v14
	v_exp_f32_e32 v13, v13
	v_exp_f32_e32 v14, v14
	s_nop 0
	v_sub_f32_e32 v13, v13, v14
	v_add_f32_e32 v13, 0x3e4ccccd, v13
	s_nop 0
	v_readfirstlane_b32 s100, v13
	s_branch .LBB0_814

; template <bool SAMPLE> __device__ __forceinline__ void attn_unit16(const Ctx& c, LAS unsigned char* lds, int b, int h, int qb, int wave_s) {
;     ...
;     if (active) {
;         float lam;
;         { const float a = c.lq1[lane2] * c.lk1[lane2], bb = c.lq2[lane2] * c.lk2[lane2]; lam = __expf(wave_sum(a)) - __expf(wave_sum(bb)) + 0.2f; }
; #pragma unroll
;         for (int qt = 0; qt < NQT; ++qt) { float l = ls[qt] + __shfl_xor(ls[qt], 16); l += __shfl_xor(l, 32);
;             const float inv = (mp ? lam : 1.f) / l;
; #pragma unroll
;             for (int i = 0; i < 4; ++i) { const float fi = __shfl(inv, 4 * q4b + i);
; #pragma unroll
;                 for (int et = 0; et < 8; ++et) o[qt][et][i] *= fi; } }
;         if (mp) {
; #pragma unroll
;             for (int qt = 0; qt < NQT; ++qt)
; #pragma unroll
;                 for (int et = 0; et < 8; ++et)
; #pragma unroll
;                     for (int i = 0; i < 4; ++i) X[(g * 64 + qt * 32 + et * 4 + i) * 64 + lane2] = o[qt][et][i];
;         }
.LBB0_884:
	s_mov_b32 s0, -1
	v_and_b32_e32 v215, 64, v212
	v_mbcnt_lo_u32_b32 v0, s0, 0
	v_mbcnt_hi_u32_b32 v0, s0, v0
	s_waitcnt vmcnt(1)
	v_add_u32_e32 v7, s33, v0
	v_xor_b32_e32 v5, 1, v212
	v_and_b32_e32 v6, 63, v7
	v_lshlrev_b32_e32 v0, 2, v6
	s_waitcnt vmcnt(0)
	v_add_u32_e32 v13, 64, v215
	v_cmp_lt_i32_e32 vcc, v5, v13
	v_xor_b32_e32 v8, 2, v212
	v_xor_b32_e32 v9, 4, v212
	v_cndmask_b32_e32 v5, v212, v5, vcc
	v_lshlrev_b32_e32 v210, 2, v5
	v_cmp_lt_i32_e32 vcc, v8, v13
	v_xor_b32_e32 v10, 8, v212
	v_xor_b32_e32 v11, 16, v212
	v_cndmask_b32_e32 v8, v212, v8, vcc
	v_lshlrev_b32_e32 v211, 2, v8
	v_cmp_lt_i32_e32 vcc, v9, v13
	v_xor_b32_e32 v12, 32, v212
	s_cmp_eq_u32 s81, 0
	v_cndmask_b32_e32 v9, v212, v9, vcc
	v_lshlrev_b32_e32 v214, 2, v9
	v_cmp_lt_i32_e32 vcc, v10, v13
	s_cselect_b64 s[2:3], -1, 0
	v_lshrrev_b32_e32 v9, 2, v7
	v_cndmask_b32_e32 v10, v212, v10, vcc
	v_cmp_lt_i32_e32 vcc, v11, v13
	v_lshlrev_b32_e32 v213, 2, v10
	s_cmp_lg_u32 s81, 0
	v_cndmask_b32_e32 v11, v212, v11, vcc
	v_cmp_lt_i32_e32 vcc, v12, v13
	v_lshlrev_b32_e32 v217, 2, v11
	ds_bpermute_b32 v8, v217, v199
	s_waitcnt lgkmcnt(0)
	v_add_f32_e32 v8, v199, v8
	s_waitcnt lgkmcnt(0)
	v_cndmask_b32_e32 v3, v212, v12, vcc
	s_waitcnt lgkmcnt(0)
	v_lshlrev_b32_e32 v216, 2, v3
	ds_bpermute_b32 v12, v216, v8
	s_waitcnt lgkmcnt(0)
	ds_bpermute_b32 v5, v217, v198
	s_waitcnt lgkmcnt(0)
	v_add_f32_e32 v5, v198, v5
	ds_bpermute_b32 v11, v216, v5
	v_and_b32_e32 v4, 12, v9
	s_waitcnt lgkmcnt(0)
	v_or_b32_e32 v9, v215, v4
	v_lshlrev_b32_e32 v9, 2, v9
	s_waitcnt lgkmcnt(0)
	v_add_f32_e32 v3, v5, v11
	v_add_f32_e32 v5, v8, v12
	v_mov_b32_e32 v0, s100
	v_cndmask_b32_e64 v0, v0, 1.0, s[2:3]
	v_div_scale_f32 v2, s[0:1], v3, v3, v0
	v_rcp_f32_e32 v11, v2
	v_div_scale_f32 v10, s[0:1], v5, v5, v0
	v_rcp_f32_e32 v12, v10
	v_fma_f32 v14, -v2, v11, 1.0
	v_div_scale_f32 v8, vcc, v0, v3, v0
	v_fmac_f32_e32 v11, v14, v11
	v_fma_f32 v15, -v10, v12, 1.0
	v_mul_f32_e32 v14, v8, v11
	v_div_scale_f32 v13, s[0:1], v0, v5, v0
	v_fmac_f32_e32 v12, v15, v12
	v_fma_f32 v16, -v2, v14, v8
	v_mul_f32_e32 v15, v13, v12
	v_fmac_f32_e32 v14, v16, v11
	v_fma_f32 v17, -v10, v15, v13
	v_fma_f32 v2, -v2, v14, v8
	v_fmac_f32_e32 v15, v17, v12
	v_div_fmas_f32 v2, v2, v11, v14
	v_fma_f32 v8, -v10, v15, v13
	v_div_fixup_f32 v2, v2, v3, v0
	s_mov_b64 vcc, s[0:1]
	v_div_fmas_f32 v3, v8, v12, v15
	ds_bpermute_b32 v8, v9, v2
	v_div_fixup_f32 v13, v3, v5, v0
	ds_bpermute_b32 v10, v9, v2 offset:4
	ds_bpermute_b32 v11, v9, v2 offset:8
	ds_bpermute_b32 v12, v9, v2 offset:12
	ds_bpermute_b32 v16, v9, v13
	s_waitcnt lgkmcnt(4)
	v_mul_f32_e32 v14, v128, v8
	v_mul_f32_e32 v15, v124, v8
	v_mul_f32_e32 v19, v116, v8
	v_mul_f32_e32 v18, v104, v8
	v_mul_f32_e32 v5, v88, v8
	v_mul_f32_e32 v3, v80, v8
	v_mul_f32_e32 v2, v68, v8
	v_mul_f32_e32 v0, v56, v8
	ds_bpermute_b32 v8, v9, v13 offset:4
	s_waitcnt lgkmcnt(4)
	v_mul_f32_e32 v113, v129, v10
	v_mul_f32_e32 v114, v125, v10
	v_mul_f32_e32 v112, v117, v10
	v_mul_f32_e32 v105, v105, v10
	v_mul_f32_e32 v104, v89, v10
	v_mul_f32_e32 v95, v81, v10
	v_mul_f32_e32 v94, v69, v10
	v_mul_f32_e32 v93, v57, v10
	s_waitcnt lgkmcnt(3)
	v_mul_f32_e32 v85, v82, v11
	v_mul_f32_e32 v82, v58, v11
	s_waitcnt lgkmcnt(2)
	v_mul_f32_e32 v69, v59, v12
	s_waitcnt lgkmcnt(1)
	v_mul_f32_e32 v59, v52, v16
	v_mul_f32_e32 v58, v48, v16
	s_waitcnt lgkmcnt(0)
	v_mul_f32_e32 v48, v121, v8
	v_mul_f32_e32 v52, v109, v8
	v_mul_f32_e32 v45, v101, v8
	v_mul_f32_e32 v44, v97, v8
	ds_bpermute_b32 v10, v9, v13 offset:8
	v_mul_f32_e32 v57, v77, v8
	v_mul_f32_e32 v56, v65, v8
	v_mul_f32_e32 v47, v53, v8
	v_mul_f32_e32 v46, v49, v8
	ds_bpermute_b32 v8, v9, v13 offset:12
	v_mul_f32_e32 v89, v130, v11
	v_mul_f32_e32 v92, v126, v11
	v_mul_f32_e32 v88, v118, v11
	v_mul_f32_e32 v87, v106, v11
	v_mul_f32_e32 v86, v90, v11
	v_mul_f32_e32 v84, v70, v11
	v_mul_f32_e32 v80, v131, v12
	v_mul_f32_e32 v81, v127, v12
	v_mul_f32_e32 v75, v119, v12
	v_mul_f32_e32 v74, v107, v12
	v_mul_f32_e32 v73, v91, v12
	v_mul_f32_e32 v72, v83, v12
	v_mul_f32_e32 v70, v71, v12
	v_mul_f32_e32 v63, v120, v16
	v_mul_f32_e32 v68, v108, v16
	v_mul_f32_e32 v61, v100, v16
	v_mul_f32_e32 v60, v96, v16
	v_mul_f32_e32 v27, v76, v16
	v_mul_f32_e32 v26, v64, v16
	s_waitcnt lgkmcnt(1)
	v_mul_f32_e32 v40, v122, v10
	v_mul_f32_e32 v41, v110, v10
	v_mul_f32_e32 v37, v102, v10
	v_mul_f32_e32 v36, v98, v10
	v_mul_f32_e32 v43, v78, v10
	v_mul_f32_e32 v42, v66, v10
	v_mul_f32_e32 v39, v54, v10
	v_mul_f32_e32 v38, v50, v10
	s_waitcnt lgkmcnt(0)
	v_mul_f32_e32 v34, v123, v8
	v_mul_f32_e32 v35, v111, v8
	v_mul_f32_e32 v33, v103, v8
	v_mul_f32_e32 v32, v99, v8
	v_mul_f32_e32 v31, v79, v8
	v_mul_f32_e32 v30, v67, v8
	v_mul_f32_e32 v29, v55, v8
	v_mul_f32_e32 v28, v51, v8
	s_cbranch_scc0 .LBB0_886
	s_lshl_b32 s0, s63, 14
	s_add_i32 s0, s0, 0
	v_lshl_add_u32 v8, v6, 2, s0
	ds_write2st64_b32 v8, v14, v113 offset1:1
	ds_write2st64_b32 v8, v89, v80 offset0:2 offset1:3
	ds_write2st64_b32 v8, v15, v114 offset0:4 offset1:5
	ds_write2st64_b32 v8, v92, v81 offset0:6 offset1:7
	ds_write2st64_b32 v8, v19, v112 offset0:8 offset1:9
	ds_write2st64_b32 v8, v88, v75 offset0:10 offset1:11
	ds_write2st64_b32 v8, v18, v105 offset0:12 offset1:13
	ds_write2st64_b32 v8, v87, v74 offset0:14 offset1:15
	ds_write2st64_b32 v8, v5, v104 offset0:16 offset1:17
	ds_write2st64_b32 v8, v86, v73 offset0:18 offset1:19
	ds_write2st64_b32 v8, v3, v95 offset0:20 offset1:21
	ds_write2st64_b32 v8, v85, v72 offset0:22 offset1:23
	ds_write2st64_b32 v8, v2, v94 offset0:24 offset1:25
	ds_write2st64_b32 v8, v84, v70 offset0:26 offset1:27
	ds_write2st64_b32 v8, v0, v93 offset0:28 offset1:29
	ds_write2st64_b32 v8, v82, v69 offset0:30 offset1:31
	ds_write2st64_b32 v8, v63, v48 offset0:32 offset1:33
	ds_write2st64_b32 v8, v40, v34 offset0:34 offset1:35
	ds_write2st64_b32 v8, v68, v52 offset0:36 offset1:37
	ds_write2st64_b32 v8, v41, v35 offset0:38 offset1:39
	ds_write2st64_b32 v8, v61, v45 offset0:40 offset1:41
	ds_write2st64_b32 v8, v37, v33 offset0:42 offset1:43
	ds_write2st64_b32 v8, v60, v44 offset0:44 offset1:45
	ds_write2st64_b32 v8, v36, v32 offset0:46 offset1:47
	ds_write2st64_b32 v8, v27, v57 offset0:48 offset1:49
	ds_write2st64_b32 v8, v43, v31 offset0:50 offset1:51
	ds_write2st64_b32 v8, v26, v56 offset0:52 offset1:53
	ds_write2st64_b32 v8, v42, v30 offset0:54 offset1:55
	ds_write2st64_b32 v8, v59, v47 offset0:56 offset1:57
	ds_write2st64_b32 v8, v39, v29 offset0:58 offset1:59
	ds_write2st64_b32 v8, v58, v46 offset0:60 offset1:61
	ds_write2st64_b32 v8, v38, v28 offset0:62 offset1:63
